# MLA: j1 rescale threshold and j0 exponent offset for the no-rescale path computed between QK MFMAs
# speedup vs baseline: 1.0077x; 1.0003x over previous
; #define LAS __attribute__((address_space(3)))
; __device__ __forceinline__ float ex2(float x) { return __builtin_amdgcn_exp2f(x); }
; __device__ __forceinline__ f32x4 mfma16(bf16x8 a, bf16x8 b, f32x4 c) { return __builtin_amdgcn_mfma_f32_16x16x32_bf16(a, b, c, 0, 0, 0); }
;   __device__ __forceinline__ bf16_t* W() const { return (bf16_t*)(ws + WS_W); }
; template <int NT, int NKK, int NDT, int MODE, bool MASK> ...
;     ...
;   f32x4 s[NT][4];
;   __builtin_amdgcn_s_setprio(1);
; #pragma unroll
;   for (int t = 0; t < 4; ++t)
; #pragma unroll
;     for (int kk = 0; kk < NKK; ++kk) {
;       const bf16x8 kf = *(LAS const bf16x8*)(Kl + (16 * t + r) * KSTR + (32 * kk + 8 * lg) * 2);
; #pragma unroll
;       for (int j = 0; j < NT; ++j) s[j][t] = mfma16(kf, qf[j][kk], kk == 0 ? (f32x4){0.f, 0.f, 0.f, 0.f} : s[j][t]);
;     }
;   __builtin_amdgcn_s_setprio(0);
;   bf16x8 pf[NT][2];
; #pragma unroll
;   for (int j = 0; j < NT; ++j) {
;     float mx = -INFINITY;
; #pragma unroll
;     for (int t = 0; t < 4; ++t)
; #pragma unroll
;       for (int i = 0; i < 4; ++i) {
;         if (MASK) { const int kp = kpos0 + 16 * t + 4 * lg + i; if (!mask_ok<MODE>(tq[j], kp, W)) s[j][t][i] = -INFINITY; }
;         mx = fmaxf(mx, s[j][t][i]);
;       }
;     mx = max_x16_x32(mx);
;     if (__any(mx > m[j] + 8.0f / c)) {
;       const float mnew = fmaxf(m[j], mx);
;       const float ms2 = (mnew == -INFINITY) ? 0.f : mnew;
;       const float alpha = ex2((m[j] - ms2) * c);
;       m[j] = mnew; l[j] *= alpha;
; #pragma unroll
;       for (int dt = 0; dt < NDT; ++dt) o[j][dt] *= alpha;
;     }
;     const float mc = ((m[j] == -INFINITY) ? 0.f : m[j]) * c;
.LBB0_768:
	s_waitcnt lgkmcnt(0)
	s_barrier
	s_add_i32 s8, s69, 0xffffff41
	s_cmp_gt_i32 s8, s68
	s_cbranch_scc1 .LBB0_797
	s_add_i32 s8, s69, 0xffffff80
	s_cmp_gt_i32 s8, s59
	s_setprio 1
	v_add_u32_e32 v1, s71, v236
	s_waitcnt lgkmcnt(0)
	v_add_u32_e32 v94, v1, v237
	ds_read_b128 v[134:137], v94
	ds_read_b128 v[130:133], v94 offset:64
	ds_read_b128 v[126:129], v94 offset:128
	ds_read_b128 v[122:125], v94 offset:3328
	ds_read_b128 v[118:121], v94 offset:3392
	ds_read_b128 v[114:117], v94 offset:3456
	ds_read_b128 v[106:109], v94 offset:6656
	ds_read_b128 v[98:101], v94 offset:6720
	v_add_u32_e32 v201, v1, v238
	ds_read_b128 v[110:113], v94 offset:6784
	ds_read_b128 v[102:105], v201
	ds_read_b128 v[94:97], v201 offset:64
	s_mov_b64 s[20:21], -1
	v_add_f32_e32 v1, 0x4259535f, v220
	s_cbranch_scc1 .LBB0_788
	s_waitcnt lgkmcnt(10)
	v_mfma_f32_16x16x32_bf16 v[138:141], v[134:137], v[18:21], 0
	ds_read_b128 v[146:149], v201 offset:128
	v_mov_b32_e32 v234, 0x260
	v_mfma_f32_16x16x32_bf16 v[142:145], v[134:137], v[10:13], 0
	s_waitcnt lgkmcnt(10)
	v_mfma_f32_16x16x32_bf16 v[138:141], v[130:133], v[2:5], v[138:141]
	v_mov_b64_e32 v[222:223], v[220:221]
	v_mfma_f32_16x16x32_bf16 v[142:145], v[130:133], v[14:17], v[142:145]
	v_mov_b64_e32 v[224:225], v[218:219]
	s_waitcnt lgkmcnt(9)
	v_mfma_f32_16x16x32_bf16 v[182:185], v[126:129], v[6:9], v[138:141]
	v_mfma_f32_16x16x32_bf16 v[166:169], v[126:129], v[22:25], v[142:145]
	v_mov_b32_e32 v187, v220
	s_waitcnt lgkmcnt(8)
	v_mfma_f32_16x16x32_bf16 v[138:141], v[122:125], v[18:21], 0
	v_add_f32_e32 v158, 0x4259535f, v221
	v_mfma_f32_16x16x32_bf16 v[142:145], v[122:125], v[10:13], 0
	v_mul_f32_e32 v159, 0x3e16c740, v220
	s_waitcnt lgkmcnt(7)
	v_mfma_f32_16x16x32_bf16 v[138:141], v[118:121], v[2:5], v[138:141]
	v_cmp_neq_f32_e64 s[22:23], s81, v220
	v_mfma_f32_16x16x32_bf16 v[142:145], v[118:121], v[14:17], v[142:145]
	s_waitcnt lgkmcnt(6)
	v_mfma_f32_16x16x32_bf16 v[178:181], v[114:117], v[6:9], v[138:141]
	v_mfma_f32_16x16x32_bf16 v[154:157], v[114:117], v[22:25], v[142:145]
	v_cndmask_b32_e64 v159, 0, v159, s[22:23]
	s_waitcnt lgkmcnt(5)
	v_mfma_f32_16x16x32_bf16 v[138:141], v[106:109], v[18:21], 0
	v_mfma_f32_16x16x32_bf16 v[142:145], v[106:109], v[10:13], 0
	v_max3_f32 v188, v182, s81, v183
	s_waitcnt lgkmcnt(4)
	v_mfma_f32_16x16x32_bf16 v[138:141], v[98:101], v[2:5], v[138:141]
	v_max3_f32 v188, v188, v184, v185
	v_mfma_f32_16x16x32_bf16 v[142:145], v[98:101], v[14:17], v[142:145]
	v_max3_f32 v189, v166, s81, v167
	s_waitcnt lgkmcnt(3)
	v_mfma_f32_16x16x32_bf16 v[174:177], v[110:113], v[6:9], v[138:141]
	v_max3_f32 v189, v189, v168, v169
	v_mfma_f32_16x16x32_bf16 v[150:153], v[110:113], v[22:25], v[142:145]
	s_waitcnt lgkmcnt(2)
	v_mfma_f32_16x16x32_bf16 v[138:141], v[102:105], v[18:21], 0
	v_mfma_f32_16x16x32_bf16 v[142:145], v[102:105], v[10:13], 0
	v_max3_f32 v188, v188, v178, v179
	s_waitcnt lgkmcnt(1)
	v_mfma_f32_16x16x32_bf16 v[138:141], v[94:97], v[2:5], v[138:141]
	v_max3_f32 v188, v188, v180, v181
	v_mfma_f32_16x16x32_bf16 v[142:145], v[94:97], v[14:17], v[142:145]
	v_max3_f32 v189, v189, v154, v155
	s_waitcnt lgkmcnt(0)
	v_mfma_f32_16x16x32_bf16 v[170:173], v[146:149], v[6:9], v[138:141]
	v_max3_f32 v189, v189, v156, v157
	v_mfma_f32_16x16x32_bf16 v[142:145], v[146:149], v[22:25], v[142:145]
	s_setprio 0
	s_nop 3
	v_max3_f32 v138, v188, v174, v175
	v_max3_f32 v138, v138, v176, v177
	v_max3_f32 v138, v138, v170, v171
	v_max3_f32 v138, v138, v172, v173
	v_mov_b32_e32 v139, v138
	s_nop 1
	v_permlane16_swap_b32_e32 v138, v139
	v_max_f32_e32 v138, v138, v139
	v_mov_b32_e32 v139, v138
	s_nop 1
	v_permlane32_swap_b32_e32 v138, v139
	v_max_f32_e32 v186, v138, v139
	v_cmp_gt_f32_e32 vcc, v186, v1
	s_cbranch_vccz .LBB0_772
	v_max_f32_e32 v138, v186, v186
	v_max_f32_e32 v139, v220, v220
	v_max_f32_e32 v222, v139, v138
	v_cmp_neq_f32_e32 vcc, s81, v222
	v_mov_b32_e32 v223, v221
	v_mov_b32_e32 v225, v219
	v_cndmask_b32_e32 v138, 0, v222, vcc
	v_sub_f32_e32 v138, v220, v138
	v_mul_f32_e32 v138, 0x3e16c740, v138
	v_exp_f32_e32 v138, v138
	v_mov_b32_e32 v187, v222
	v_mul_f32_e32 v224, v218, v138
	v_pk_mul_f32 v[92:93], v[92:93], v[138:139] op_sel_hi:[1,0]
	v_pk_mul_f32 v[90:91], v[90:91], v[138:139] op_sel_hi:[1,0]
	v_pk_mul_f32 v[88:89], v[88:89], v[138:139] op_sel_hi:[1,0]
	v_pk_mul_f32 v[86:87], v[86:87], v[138:139] op_sel_hi:[1,0]
	v_pk_mul_f32 v[76:77], v[76:77], v[138:139] op_sel_hi:[1,0]
	v_pk_mul_f32 v[74:75], v[74:75], v[138:139] op_sel_hi:[1,0]
	v_pk_mul_f32 v[68:69], v[68:69], v[138:139] op_sel_hi:[1,0]
	v_pk_mul_f32 v[66:67], v[66:67], v[138:139] op_sel_hi:[1,0]
	v_mul_f32_e32 v159, 0x3e16c740, v187
	v_cmp_neq_f32_e32 vcc, s81, v187
	s_nop 1
	v_cndmask_b32_e32 v159, 0, v159, vcc
; __device__ __forceinline__ float ex2(float x) { return __builtin_amdgcn_exp2f(x); }
;   __device__ __forceinline__ bf16_t* W() const { return (bf16_t*)(ws + WS_W); }
; template <int NT, int NKK, int NDT, int MODE, bool MASK> ...
;     ...
;   for (int j = 0; j < NT; ++j) {
;     float mx = -INFINITY;
; #pragma unroll
;     for (int t = 0; t < 4; ++t)
; #pragma unroll
;       for (int i = 0; i < 4; ++i) {
;         if (MASK) { const int kp = kpos0 + 16 * t + 4 * lg + i; if (!mask_ok<MODE>(tq[j], kp, W)) s[j][t][i] = -INFINITY; }
;         mx = fmaxf(mx, s[j][t][i]);
;       }
;     mx = max_x16_x32(mx);
;     if (__any(mx > m[j] + 8.0f / c)) {
;     ...
;     const float mc = ((m[j] == -INFINITY) ? 0.f : m[j]) * c;
;     float p[4][4], ps = 0.f;
; #pragma unroll
;     for (int t = 0; t < 4; ++t)
; #pragma unroll
;       for (int i = 0; i < 4; ++i) { p[t][i] = ex2(s[j][t][i] * c - mc); ps += p[t][i]; }
;     l[j] += ps;
.LBB0_772:
	v_fma_f32 v182, v182, s88, -v159
	v_exp_f32_e32 v205, v182
	v_fma_f32 v182, v183, s88, -v159
	v_exp_f32_e32 v207, v182
	v_fma_f32 v182, v184, s88, -v159
	v_exp_f32_e32 v246, v182
	v_fma_f32 v182, v185, s88, -v159
	v_exp_f32_e32 v247, v182
	v_fma_f32 v178, v178, s88, -v159
	v_exp_f32_e32 v248, v178
	v_fma_f32 v178, v179, s88, -v159
	v_add_f32_e32 v182, v207, v205
	v_exp_f32_e32 v249, v178
	v_fma_f32 v178, v180, s88, -v159
	v_add_f32_e32 v182, v246, v182
	v_exp_f32_e32 v250, v178
	v_fma_f32 v178, v181, s88, -v159
	v_add_f32_e32 v182, v247, v182
	v_exp_f32_e32 v251, v178
	v_fma_f32 v174, v174, s88, -v159
	v_add_f32_e32 v178, v248, v182
	v_exp_f32_e32 v252, v174
	v_fma_f32 v174, v175, s88, -v159
	v_add_f32_e32 v178, v249, v178
	v_exp_f32_e32 v231, v174
	v_fma_f32 v174, v176, s88, -v159
	v_add_f32_e32 v178, v250, v178
	v_exp_f32_e32 v229, v174
	v_fma_f32 v174, v177, s88, -v159
	v_add_f32_e32 v178, v251, v178
	v_exp_f32_e32 v230, v174
	v_fma_f32 v170, v170, s88, -v159
	v_add_f32_e32 v174, v252, v178
	v_exp_f32_e32 v232, v170
	v_fma_f32 v170, v171, s88, -v159
	v_add_f32_e32 v174, v231, v174
	v_exp_f32_e32 v228, v170
	v_fma_f32 v170, v172, s88, -v159
	v_add_f32_e32 v174, v229, v174
	v_exp_f32_e32 v196, v170
	v_fma_f32 v170, v173, s88, -v159
	v_add_f32_e32 v174, v230, v174
	v_exp_f32_e32 v173, v170
	v_add_f32_e32 v170, v232, v174
	v_add_f32_e32 v170, v228, v170
	v_add_f32_e32 v170, v196, v170
	v_add_f32_e32 v170, v173, v170
	v_add_f32_e32 v224, v224, v170
	v_max3_f32 v170, v189, v150, v151
	v_max3_f32 v170, v170, v152, v153
	v_max3_f32 v170, v170, v142, v143
	v_max3_f32 v170, v170, v144, v145
	v_mov_b32_e32 v171, v170
	s_nop 1
	v_permlane16_swap_b32_e32 v170, v171
	v_max_f32_e32 v170, v170, v171
	v_mov_b32_e32 v171, v170
	s_nop 1
	v_permlane32_swap_b32_e32 v170, v171
	v_max_f32_e32 v170, v170, v171
	v_cmp_gt_f32_e32 vcc, v170, v158
	s_cbranch_vccz .LBB0_786
	v_max_f32_e32 v170, v170, v170
	v_max_f32_e32 v171, v223, v223
	v_max_f32_e32 v197, v171, v170
	v_cmp_neq_f32_e32 vcc, s81, v197
	s_nop 1
	v_cndmask_b32_e32 v170, 0, v197, vcc
	v_sub_f32_e32 v170, v223, v170
	v_mul_f32_e32 v170, 0x3e16c740, v170
	v_exp_f32_e32 v170, v170
	v_mov_b32_e32 v223, v197
	v_mul_f32_e32 v225, v225, v170
	v_pk_mul_f32 v[84:85], v[84:85], v[170:171] op_sel_hi:[1,0]
	v_pk_mul_f32 v[82:83], v[82:83], v[170:171] op_sel_hi:[1,0]
	v_pk_mul_f32 v[80:81], v[80:81], v[170:171] op_sel_hi:[1,0]
	v_pk_mul_f32 v[78:79], v[78:79], v[170:171] op_sel_hi:[1,0]
	v_pk_mul_f32 v[72:73], v[72:73], v[170:171] op_sel_hi:[1,0]
	v_pk_mul_f32 v[70:71], v[70:71], v[170:171] op_sel_hi:[1,0]
	v_pk_mul_f32 v[64:65], v[64:65], v[170:171] op_sel_hi:[1,0]
	v_pk_mul_f32 v[62:63], v[62:63], v[170:171] op_sel_hi:[1,0]
	s_branch .LBB0_787

; #define LAS __attribute__((address_space(3)))
; __device__ __forceinline__ float ex2(float x) { return __builtin_amdgcn_exp2f(x); }
; __device__ __forceinline__ f32x4 mfma16(bf16x8 a, bf16x8 b, f32x4 c) { return __builtin_amdgcn_mfma_f32_16x16x32_bf16(a, b, c, 0, 0, 0); }
;   __device__ __forceinline__ bf16_t* W() const { return (bf16_t*)(ws + WS_W); }
; template <int NT, int NKK, int NDT, int MODE, bool MASK> ...
;     ...
;   f32x4 s[NT][4];
;   __builtin_amdgcn_s_setprio(1);
; #pragma unroll
;   for (int t = 0; t < 4; ++t)
; #pragma unroll
;     for (int kk = 0; kk < NKK; ++kk) {
;       const bf16x8 kf = *(LAS const bf16x8*)(Kl + (16 * t + r) * KSTR + (32 * kk + 8 * lg) * 2);
; #pragma unroll
;       for (int j = 0; j < NT; ++j) s[j][t] = mfma16(kf, qf[j][kk], kk == 0 ? (f32x4){0.f, 0.f, 0.f, 0.f} : s[j][t]);
;     }
;   __builtin_amdgcn_s_setprio(0);
;   bf16x8 pf[NT][2];
; #pragma unroll
;   for (int j = 0; j < NT; ++j) {
;     float mx = -INFINITY;
; #pragma unroll
;     for (int t = 0; t < 4; ++t)
; #pragma unroll
;       for (int i = 0; i < 4; ++i) {
;         if (MASK) { const int kp = kpos0 + 16 * t + 4 * lg + i; if (!mask_ok<MODE>(tq[j], kp, W)) s[j][t][i] = -INFINITY; }
;         mx = fmaxf(mx, s[j][t][i]);
;       }
;     mx = max_x16_x32(mx);
;     if (__any(mx > m[j] + 8.0f / c)) {
;       const float mnew = fmaxf(m[j], mx);
;       const float ms2 = (mnew == -INFINITY) ? 0.f : mnew;
;       const float alpha = ex2((m[j] - ms2) * c);
;       m[j] = mnew; l[j] *= alpha;
; #pragma unroll
;       for (int dt = 0; dt < NDT; ++dt) o[j][dt] *= alpha;
;     }
;     const float mc = ((m[j] == -INFINITY) ? 0.f : m[j]) * c;
.LBB0_810:
	s_waitcnt lgkmcnt(0)
	s_barrier
	s_add_i32 s8, s69, 0xffffff81
	s_cmp_gt_i32 s8, s68
	s_cbranch_scc1 .LBB0_837
	s_sub_i32 s8, s69, 64
	s_cmp_gt_i32 s8, s59
	s_setprio 1
	v_add_u32_e32 v1, s73, v236
	s_waitcnt lgkmcnt(0)
	v_add_u32_e32 v94, v1, v237
	ds_read_b128 v[134:137], v94
	ds_read_b128 v[130:133], v94 offset:64
	ds_read_b128 v[126:129], v94 offset:128
	ds_read_b128 v[122:125], v94 offset:3328
	ds_read_b128 v[118:121], v94 offset:3392
	ds_read_b128 v[114:117], v94 offset:3456
	ds_read_b128 v[106:109], v94 offset:6656
	ds_read_b128 v[98:101], v94 offset:6720
	v_add_u32_e32 v201, v1, v238
	ds_read_b128 v[110:113], v94 offset:6784
	ds_read_b128 v[102:105], v201
	ds_read_b128 v[94:97], v201 offset:64
	s_mov_b64 s[20:21], -1
	v_add_f32_e32 v1, 0x4259535f, v220
	s_cbranch_scc1 .LBB0_828
	s_waitcnt lgkmcnt(10)
	v_mfma_f32_16x16x32_bf16 v[138:141], v[134:137], v[18:21], 0
	ds_read_b128 v[146:149], v201 offset:128
	v_mov_b32_e32 v234, 0x260
	v_mfma_f32_16x16x32_bf16 v[142:145], v[134:137], v[10:13], 0
	s_waitcnt lgkmcnt(10)
	v_mfma_f32_16x16x32_bf16 v[138:141], v[130:133], v[2:5], v[138:141]
	v_mov_b64_e32 v[222:223], v[220:221]
	v_mfma_f32_16x16x32_bf16 v[142:145], v[130:133], v[14:17], v[142:145]
	v_mov_b64_e32 v[224:225], v[218:219]
	s_waitcnt lgkmcnt(9)
	v_mfma_f32_16x16x32_bf16 v[182:185], v[126:129], v[6:9], v[138:141]
	v_mfma_f32_16x16x32_bf16 v[166:169], v[126:129], v[22:25], v[142:145]
	v_mov_b32_e32 v187, v220
	s_waitcnt lgkmcnt(8)
	v_mfma_f32_16x16x32_bf16 v[138:141], v[122:125], v[18:21], 0
	v_add_f32_e32 v158, 0x4259535f, v221
	v_mfma_f32_16x16x32_bf16 v[142:145], v[122:125], v[10:13], 0
	v_mul_f32_e32 v159, 0x3e16c740, v220
	s_waitcnt lgkmcnt(7)
	v_mfma_f32_16x16x32_bf16 v[138:141], v[118:121], v[2:5], v[138:141]
	v_cmp_neq_f32_e64 s[22:23], s81, v220
	v_mfma_f32_16x16x32_bf16 v[142:145], v[118:121], v[14:17], v[142:145]
	s_waitcnt lgkmcnt(6)
	v_mfma_f32_16x16x32_bf16 v[178:181], v[114:117], v[6:9], v[138:141]
	v_mfma_f32_16x16x32_bf16 v[154:157], v[114:117], v[22:25], v[142:145]
	v_cndmask_b32_e64 v159, 0, v159, s[22:23]
	s_waitcnt lgkmcnt(5)
	v_mfma_f32_16x16x32_bf16 v[138:141], v[106:109], v[18:21], 0
	v_mfma_f32_16x16x32_bf16 v[142:145], v[106:109], v[10:13], 0
	v_max3_f32 v188, v182, s81, v183
	s_waitcnt lgkmcnt(4)
	v_mfma_f32_16x16x32_bf16 v[138:141], v[98:101], v[2:5], v[138:141]
	v_max3_f32 v188, v188, v184, v185
	v_mfma_f32_16x16x32_bf16 v[142:145], v[98:101], v[14:17], v[142:145]
	v_max3_f32 v189, v166, s81, v167
	s_waitcnt lgkmcnt(3)
	v_mfma_f32_16x16x32_bf16 v[174:177], v[110:113], v[6:9], v[138:141]
	v_max3_f32 v189, v189, v168, v169
	v_mfma_f32_16x16x32_bf16 v[150:153], v[110:113], v[22:25], v[142:145]
	s_waitcnt lgkmcnt(2)
	v_mfma_f32_16x16x32_bf16 v[138:141], v[102:105], v[18:21], 0
	v_mfma_f32_16x16x32_bf16 v[142:145], v[102:105], v[10:13], 0
	v_max3_f32 v188, v188, v178, v179
	s_waitcnt lgkmcnt(1)
	v_mfma_f32_16x16x32_bf16 v[138:141], v[94:97], v[2:5], v[138:141]
	v_max3_f32 v188, v188, v180, v181
	v_mfma_f32_16x16x32_bf16 v[142:145], v[94:97], v[14:17], v[142:145]
	v_max3_f32 v189, v189, v154, v155
	s_waitcnt lgkmcnt(0)
	v_mfma_f32_16x16x32_bf16 v[170:173], v[146:149], v[6:9], v[138:141]
	v_max3_f32 v189, v189, v156, v157
	v_mfma_f32_16x16x32_bf16 v[142:145], v[146:149], v[22:25], v[142:145]
	s_setprio 0
	s_nop 3
	v_max3_f32 v138, v188, v174, v175
	v_max3_f32 v138, v138, v176, v177
	v_max3_f32 v138, v138, v170, v171
	v_max3_f32 v138, v138, v172, v173
	v_mov_b32_e32 v139, v138
	s_nop 1
	v_permlane16_swap_b32_e32 v138, v139
	v_max_f32_e32 v138, v138, v139
	v_mov_b32_e32 v139, v138
	s_nop 1
	v_permlane32_swap_b32_e32 v138, v139
	v_max_f32_e32 v186, v138, v139
	v_cmp_gt_f32_e32 vcc, v186, v1
	s_cbranch_vccz .LBB0_814
	v_max_f32_e32 v138, v186, v186
	v_max_f32_e32 v139, v220, v220
	v_max_f32_e32 v222, v139, v138
	v_cmp_neq_f32_e32 vcc, s81, v222
	v_mov_b32_e32 v223, v221
	v_mov_b32_e32 v225, v219
	v_cndmask_b32_e32 v138, 0, v222, vcc
	v_sub_f32_e32 v138, v220, v138
	v_mul_f32_e32 v138, 0x3e16c740, v138
	v_exp_f32_e32 v138, v138
	v_mov_b32_e32 v187, v222
	v_mul_f32_e32 v224, v218, v138
	v_pk_mul_f32 v[92:93], v[92:93], v[138:139] op_sel_hi:[1,0]
	v_pk_mul_f32 v[90:91], v[90:91], v[138:139] op_sel_hi:[1,0]
	v_pk_mul_f32 v[88:89], v[88:89], v[138:139] op_sel_hi:[1,0]
	v_pk_mul_f32 v[86:87], v[86:87], v[138:139] op_sel_hi:[1,0]
	v_pk_mul_f32 v[76:77], v[76:77], v[138:139] op_sel_hi:[1,0]
	v_pk_mul_f32 v[74:75], v[74:75], v[138:139] op_sel_hi:[1,0]
	v_pk_mul_f32 v[68:69], v[68:69], v[138:139] op_sel_hi:[1,0]
	v_pk_mul_f32 v[66:67], v[66:67], v[138:139] op_sel_hi:[1,0]
	v_mul_f32_e32 v159, 0x3e16c740, v187
	v_cmp_neq_f32_e32 vcc, s81, v187
	s_nop 1
	v_cndmask_b32_e32 v159, 0, v159, vcc

; #define LAS __attribute__((address_space(3)))
; __device__ __forceinline__ float ex2(float x) { return __builtin_amdgcn_exp2f(x); }
; __device__ __forceinline__ f32x4 mfma16(bf16x8 a, bf16x8 b, f32x4 c) { return __builtin_amdgcn_mfma_f32_16x16x32_bf16(a, b, c, 0, 0, 0); }
;   __device__ __forceinline__ bf16_t* W() const { return (bf16_t*)(ws + WS_W); }
; template <int NT, int NKK, int NDT, int MODE, bool MASK> ...
;     ...
;   f32x4 s[NT][4];
;   __builtin_amdgcn_s_setprio(1);
; #pragma unroll
;   for (int t = 0; t < 4; ++t)
; #pragma unroll
;     for (int kk = 0; kk < NKK; ++kk) {
;       const bf16x8 kf = *(LAS const bf16x8*)(Kl + (16 * t + r) * KSTR + (32 * kk + 8 * lg) * 2);
; #pragma unroll
;       for (int j = 0; j < NT; ++j) s[j][t] = mfma16(kf, qf[j][kk], kk == 0 ? (f32x4){0.f, 0.f, 0.f, 0.f} : s[j][t]);
;     }
;   __builtin_amdgcn_s_setprio(0);
;   bf16x8 pf[NT][2];
; #pragma unroll
;   for (int j = 0; j < NT; ++j) {
;     float mx = -INFINITY;
; #pragma unroll
;     for (int t = 0; t < 4; ++t)
; #pragma unroll
;       for (int i = 0; i < 4; ++i) {
;         if (MASK) { const int kp = kpos0 + 16 * t + 4 * lg + i; if (!mask_ok<MODE>(tq[j], kp, W)) s[j][t][i] = -INFINITY; }
;         mx = fmaxf(mx, s[j][t][i]);
;       }
;     mx = max_x16_x32(mx);
;     if (__any(mx > m[j] + 8.0f / c)) {
;       const float mnew = fmaxf(m[j], mx);
;       const float ms2 = (mnew == -INFINITY) ? 0.f : mnew;
;       const float alpha = ex2((m[j] - ms2) * c);
;       m[j] = mnew; l[j] *= alpha;
; #pragma unroll
;       for (int dt = 0; dt < NDT; ++dt) o[j][dt] *= alpha;
;     }
;     const float mc = ((m[j] == -INFINITY) ? 0.f : m[j]) * c;
.LBB0_850:
	s_waitcnt lgkmcnt(0)
	s_barrier
	s_sub_i32 s8, s69, 63
	s_cmp_gt_i32 s8, s68
	s_cbranch_scc1 .LBB0_877
	s_cmp_gt_i32 s69, s59
	s_setprio 1
	v_add_u32_e32 v1, s71, v236
	s_waitcnt lgkmcnt(0)
	v_add_u32_e32 v94, v1, v237
	ds_read_b128 v[134:137], v94
	ds_read_b128 v[130:133], v94 offset:64
	ds_read_b128 v[126:129], v94 offset:128
	ds_read_b128 v[122:125], v94 offset:3328
	ds_read_b128 v[118:121], v94 offset:3392
	ds_read_b128 v[114:117], v94 offset:3456
	ds_read_b128 v[106:109], v94 offset:6656
	ds_read_b128 v[98:101], v94 offset:6720
	v_add_u32_e32 v201, v1, v238
	ds_read_b128 v[110:113], v94 offset:6784
	ds_read_b128 v[102:105], v201
	ds_read_b128 v[94:97], v201 offset:64
	s_mov_b64 s[20:21], -1
	v_add_f32_e32 v1, 0x4259535f, v220
	s_cbranch_scc1 .LBB0_868
	s_waitcnt lgkmcnt(10)
	v_mfma_f32_16x16x32_bf16 v[138:141], v[134:137], v[18:21], 0
	ds_read_b128 v[146:149], v201 offset:128
	v_mov_b32_e32 v234, 0x260
	v_mfma_f32_16x16x32_bf16 v[142:145], v[134:137], v[10:13], 0
	s_waitcnt lgkmcnt(10)
	v_mfma_f32_16x16x32_bf16 v[138:141], v[130:133], v[2:5], v[138:141]
	v_mov_b64_e32 v[222:223], v[220:221]
	v_mfma_f32_16x16x32_bf16 v[142:145], v[130:133], v[14:17], v[142:145]
	v_mov_b64_e32 v[224:225], v[218:219]
	s_waitcnt lgkmcnt(9)
	v_mfma_f32_16x16x32_bf16 v[182:185], v[126:129], v[6:9], v[138:141]
	v_mfma_f32_16x16x32_bf16 v[166:169], v[126:129], v[22:25], v[142:145]
	v_mov_b32_e32 v187, v220
	s_waitcnt lgkmcnt(8)
	v_mfma_f32_16x16x32_bf16 v[138:141], v[122:125], v[18:21], 0
	v_add_f32_e32 v158, 0x4259535f, v221
	v_mfma_f32_16x16x32_bf16 v[142:145], v[122:125], v[10:13], 0
	v_mul_f32_e32 v159, 0x3e16c740, v220
	s_waitcnt lgkmcnt(7)
	v_mfma_f32_16x16x32_bf16 v[138:141], v[118:121], v[2:5], v[138:141]
	v_cmp_neq_f32_e64 s[22:23], s81, v220
	v_mfma_f32_16x16x32_bf16 v[142:145], v[118:121], v[14:17], v[142:145]
	s_waitcnt lgkmcnt(6)
	v_mfma_f32_16x16x32_bf16 v[178:181], v[114:117], v[6:9], v[138:141]
	v_mfma_f32_16x16x32_bf16 v[154:157], v[114:117], v[22:25], v[142:145]
	v_cndmask_b32_e64 v159, 0, v159, s[22:23]
	s_waitcnt lgkmcnt(5)
	v_mfma_f32_16x16x32_bf16 v[138:141], v[106:109], v[18:21], 0
	v_mfma_f32_16x16x32_bf16 v[142:145], v[106:109], v[10:13], 0
	v_max3_f32 v188, v182, s81, v183
	s_waitcnt lgkmcnt(4)
	v_mfma_f32_16x16x32_bf16 v[138:141], v[98:101], v[2:5], v[138:141]
	v_max3_f32 v188, v188, v184, v185
	v_mfma_f32_16x16x32_bf16 v[142:145], v[98:101], v[14:17], v[142:145]
	v_max3_f32 v189, v166, s81, v167
	s_waitcnt lgkmcnt(3)
	v_mfma_f32_16x16x32_bf16 v[174:177], v[110:113], v[6:9], v[138:141]
	v_max3_f32 v189, v189, v168, v169
	v_mfma_f32_16x16x32_bf16 v[150:153], v[110:113], v[22:25], v[142:145]
	s_waitcnt lgkmcnt(2)
	v_mfma_f32_16x16x32_bf16 v[138:141], v[102:105], v[18:21], 0
	v_mfma_f32_16x16x32_bf16 v[142:145], v[102:105], v[10:13], 0
	v_max3_f32 v188, v188, v178, v179
	s_waitcnt lgkmcnt(1)
	v_mfma_f32_16x16x32_bf16 v[138:141], v[94:97], v[2:5], v[138:141]
	v_max3_f32 v188, v188, v180, v181
	v_mfma_f32_16x16x32_bf16 v[142:145], v[94:97], v[14:17], v[142:145]
	v_max3_f32 v189, v189, v154, v155
	s_waitcnt lgkmcnt(0)
	v_mfma_f32_16x16x32_bf16 v[170:173], v[146:149], v[6:9], v[138:141]
	v_max3_f32 v189, v189, v156, v157
	v_mfma_f32_16x16x32_bf16 v[142:145], v[146:149], v[22:25], v[142:145]
	s_setprio 0
	s_nop 3
	v_max3_f32 v138, v188, v174, v175
	v_max3_f32 v138, v138, v176, v177
	v_max3_f32 v138, v138, v170, v171
	v_max3_f32 v138, v138, v172, v173
	v_mov_b32_e32 v139, v138
	s_nop 1
	v_permlane16_swap_b32_e32 v138, v139
	v_max_f32_e32 v138, v138, v139
	v_mov_b32_e32 v139, v138
	s_nop 1
	v_permlane32_swap_b32_e32 v138, v139
	v_max_f32_e32 v186, v138, v139
	v_cmp_gt_f32_e32 vcc, v186, v1
	s_cbranch_vccz .LBB0_854
	v_max_f32_e32 v138, v186, v186
	v_max_f32_e32 v139, v220, v220
	v_max_f32_e32 v222, v139, v138
	v_cmp_neq_f32_e32 vcc, s81, v222
	v_mov_b32_e32 v223, v221
	v_mov_b32_e32 v225, v219
	v_cndmask_b32_e32 v138, 0, v222, vcc
	v_sub_f32_e32 v138, v220, v138
	v_mul_f32_e32 v138, 0x3e16c740, v138
	v_exp_f32_e32 v138, v138
	v_mov_b32_e32 v187, v222
	v_mul_f32_e32 v224, v218, v138
	v_pk_mul_f32 v[92:93], v[92:93], v[138:139] op_sel_hi:[1,0]
	v_pk_mul_f32 v[90:91], v[90:91], v[138:139] op_sel_hi:[1,0]
	v_pk_mul_f32 v[88:89], v[88:89], v[138:139] op_sel_hi:[1,0]
	v_pk_mul_f32 v[86:87], v[86:87], v[138:139] op_sel_hi:[1,0]
	v_pk_mul_f32 v[76:77], v[76:77], v[138:139] op_sel_hi:[1,0]
	v_pk_mul_f32 v[74:75], v[74:75], v[138:139] op_sel_hi:[1,0]
	v_pk_mul_f32 v[68:69], v[68:69], v[138:139] op_sel_hi:[1,0]
	v_pk_mul_f32 v[66:67], v[66:67], v[138:139] op_sel_hi:[1,0]
	v_mul_f32_e32 v159, 0x3e16c740, v187
	v_cmp_neq_f32_e32 vcc, s81, v187
	s_nop 1
	v_cndmask_b32_e32 v159, 0, v159, vcc

; #define LAS __attribute__((address_space(3)))
; __device__ __forceinline__ float ex2(float x) { return __builtin_amdgcn_exp2f(x); }
; __device__ __forceinline__ f32x4 mfma16(bf16x8 a, bf16x8 b, f32x4 c) { return __builtin_amdgcn_mfma_f32_16x16x32_bf16(a, b, c, 0, 0, 0); }
;   __device__ __forceinline__ bf16_t* W() const { return (bf16_t*)(ws + WS_W); }
; template <int NT, int NKK, int NDT, int MODE, bool MASK> ...
;     ...
;   f32x4 s[NT][4];
;   __builtin_amdgcn_s_setprio(1);
; #pragma unroll
;   for (int t = 0; t < 4; ++t)
; #pragma unroll
;     for (int kk = 0; kk < NKK; ++kk) {
;       const bf16x8 kf = *(LAS const bf16x8*)(Kl + (16 * t + r) * KSTR + (32 * kk + 8 * lg) * 2);
; #pragma unroll
;       for (int j = 0; j < NT; ++j) s[j][t] = mfma16(kf, qf[j][kk], kk == 0 ? (f32x4){0.f, 0.f, 0.f, 0.f} : s[j][t]);
;     }
;   __builtin_amdgcn_s_setprio(0);
;   bf16x8 pf[NT][2];
; #pragma unroll
;   for (int j = 0; j < NT; ++j) {
;     float mx = -INFINITY;
; #pragma unroll
;     for (int t = 0; t < 4; ++t)
; #pragma unroll
;       for (int i = 0; i < 4; ++i) {
;         if (MASK) { const int kp = kpos0 + 16 * t + 4 * lg + i; if (!mask_ok<MODE>(tq[j], kp, W)) s[j][t][i] = -INFINITY; }
;         mx = fmaxf(mx, s[j][t][i]);
;       }
;     mx = max_x16_x32(mx);
;     if (__any(mx > m[j] + 8.0f / c)) {
;       const float mnew = fmaxf(m[j], mx);
;       const float ms2 = (mnew == -INFINITY) ? 0.f : mnew;
;       const float alpha = ex2((m[j] - ms2) * c);
;       m[j] = mnew; l[j] *= alpha;
; #pragma unroll
;       for (int dt = 0; dt < NDT; ++dt) o[j][dt] *= alpha;
;     }
;     const float mc = ((m[j] == -INFINITY) ? 0.f : m[j]) * c;
.LBB0_941:
	s_waitcnt lgkmcnt(0)
	s_barrier
	s_add_i32 s8, s43, 0xffffff41
	s_cmp_gt_i32 s8, s40
	s_cbranch_scc1 .LBB0_970
	s_add_i32 s8, s43, 0xffffff80
	s_cmp_gt_i32 s8, s25
	s_setprio 1
	v_add_u32_e32 v1, s45, v236
	s_waitcnt lgkmcnt(0)
	v_add_u32_e32 v94, v1, v237
	ds_read_b128 v[134:137], v94
	ds_read_b128 v[130:133], v94 offset:64
	ds_read_b128 v[126:129], v94 offset:128
	ds_read_b128 v[122:125], v94 offset:3328
	ds_read_b128 v[118:121], v94 offset:3392
	ds_read_b128 v[114:117], v94 offset:3456
	ds_read_b128 v[106:109], v94 offset:6656
	ds_read_b128 v[98:101], v94 offset:6720
	v_add_u32_e32 v201, v1, v238
	ds_read_b128 v[110:113], v94 offset:6784
	ds_read_b128 v[102:105], v201
	ds_read_b128 v[94:97], v201 offset:64
	s_mov_b64 s[20:21], -1
	v_add_f32_e32 v1, 0x4259535f, v220
	s_cbranch_scc1 .LBB0_961
	s_waitcnt lgkmcnt(10)
	v_mfma_f32_16x16x32_bf16 v[138:141], v[134:137], v[18:21], 0
	ds_read_b128 v[146:149], v201 offset:128
	v_mov_b32_e32 v234, 0x260
	v_mfma_f32_16x16x32_bf16 v[142:145], v[134:137], v[10:13], 0
	s_waitcnt lgkmcnt(10)
	v_mfma_f32_16x16x32_bf16 v[138:141], v[130:133], v[2:5], v[138:141]
	v_mov_b64_e32 v[222:223], v[220:221]
	v_mfma_f32_16x16x32_bf16 v[142:145], v[130:133], v[14:17], v[142:145]
	v_mov_b64_e32 v[224:225], v[218:219]
	s_waitcnt lgkmcnt(9)
	v_mfma_f32_16x16x32_bf16 v[182:185], v[126:129], v[6:9], v[138:141]
	v_mfma_f32_16x16x32_bf16 v[166:169], v[126:129], v[22:25], v[142:145]
	v_mov_b32_e32 v187, v220
	s_waitcnt lgkmcnt(8)
	v_mfma_f32_16x16x32_bf16 v[138:141], v[122:125], v[18:21], 0
	v_add_f32_e32 v158, 0x4259535f, v221
	v_mfma_f32_16x16x32_bf16 v[142:145], v[122:125], v[10:13], 0
	v_mul_f32_e32 v159, 0x3e16c740, v220
	s_waitcnt lgkmcnt(7)
	v_mfma_f32_16x16x32_bf16 v[138:141], v[118:121], v[2:5], v[138:141]
	v_cmp_neq_f32_e64 s[22:23], s81, v220
	v_mfma_f32_16x16x32_bf16 v[142:145], v[118:121], v[14:17], v[142:145]
	s_waitcnt lgkmcnt(6)
	v_mfma_f32_16x16x32_bf16 v[178:181], v[114:117], v[6:9], v[138:141]
	v_mfma_f32_16x16x32_bf16 v[154:157], v[114:117], v[22:25], v[142:145]
	v_cndmask_b32_e64 v159, 0, v159, s[22:23]
	s_waitcnt lgkmcnt(5)
	v_mfma_f32_16x16x32_bf16 v[138:141], v[106:109], v[18:21], 0
	v_mfma_f32_16x16x32_bf16 v[142:145], v[106:109], v[10:13], 0
	v_max3_f32 v188, v182, s81, v183
	s_waitcnt lgkmcnt(4)
	v_mfma_f32_16x16x32_bf16 v[138:141], v[98:101], v[2:5], v[138:141]
	v_max3_f32 v188, v188, v184, v185
	v_mfma_f32_16x16x32_bf16 v[142:145], v[98:101], v[14:17], v[142:145]
	v_max3_f32 v189, v166, s81, v167
	s_waitcnt lgkmcnt(3)
	v_mfma_f32_16x16x32_bf16 v[174:177], v[110:113], v[6:9], v[138:141]
	v_max3_f32 v189, v189, v168, v169
	v_mfma_f32_16x16x32_bf16 v[150:153], v[110:113], v[22:25], v[142:145]
	s_waitcnt lgkmcnt(2)
	v_mfma_f32_16x16x32_bf16 v[138:141], v[102:105], v[18:21], 0
	v_mfma_f32_16x16x32_bf16 v[142:145], v[102:105], v[10:13], 0
	v_max3_f32 v188, v188, v178, v179
	s_waitcnt lgkmcnt(1)
	v_mfma_f32_16x16x32_bf16 v[138:141], v[94:97], v[2:5], v[138:141]
	v_max3_f32 v188, v188, v180, v181
	v_mfma_f32_16x16x32_bf16 v[142:145], v[94:97], v[14:17], v[142:145]
	v_max3_f32 v189, v189, v154, v155
	s_waitcnt lgkmcnt(0)
	v_mfma_f32_16x16x32_bf16 v[170:173], v[146:149], v[6:9], v[138:141]
	v_max3_f32 v189, v189, v156, v157
	v_mfma_f32_16x16x32_bf16 v[142:145], v[146:149], v[22:25], v[142:145]
	s_setprio 0
	s_nop 3
	v_max3_f32 v138, v188, v174, v175
	v_max3_f32 v138, v138, v176, v177
	v_max3_f32 v138, v138, v170, v171
	v_max3_f32 v138, v138, v172, v173
	v_mov_b32_e32 v139, v138
	s_nop 1
	v_permlane16_swap_b32_e32 v138, v139
	v_max_f32_e32 v138, v138, v139
	v_mov_b32_e32 v139, v138
	s_nop 1
	v_permlane32_swap_b32_e32 v138, v139
	v_max_f32_e32 v186, v138, v139
	v_cmp_gt_f32_e32 vcc, v186, v1
	s_cbranch_vccz .LBB0_945
	v_max_f32_e32 v138, v186, v186
	v_max_f32_e32 v139, v220, v220
	v_max_f32_e32 v222, v139, v138
	v_cmp_neq_f32_e32 vcc, s81, v222
	v_mov_b32_e32 v223, v221
	v_mov_b32_e32 v225, v219
	v_cndmask_b32_e32 v138, 0, v222, vcc
	v_sub_f32_e32 v138, v220, v138
	v_mul_f32_e32 v138, 0x3e16c740, v138
	v_exp_f32_e32 v138, v138
	v_mov_b32_e32 v187, v222
	v_mul_f32_e32 v224, v218, v138
	v_pk_mul_f32 v[92:93], v[92:93], v[138:139] op_sel_hi:[1,0]
	v_pk_mul_f32 v[90:91], v[90:91], v[138:139] op_sel_hi:[1,0]
	v_pk_mul_f32 v[88:89], v[88:89], v[138:139] op_sel_hi:[1,0]
	v_pk_mul_f32 v[86:87], v[86:87], v[138:139] op_sel_hi:[1,0]
	v_pk_mul_f32 v[76:77], v[76:77], v[138:139] op_sel_hi:[1,0]
	v_pk_mul_f32 v[74:75], v[74:75], v[138:139] op_sel_hi:[1,0]
	v_pk_mul_f32 v[68:69], v[68:69], v[138:139] op_sel_hi:[1,0]
	v_pk_mul_f32 v[66:67], v[66:67], v[138:139] op_sel_hi:[1,0]
	v_mul_f32_e32 v159, 0x3e16c740, v187
	v_cmp_neq_f32_e32 vcc, s81, v187
	s_nop 1
	v_cndmask_b32_e32 v159, 0, v159, vcc

; #define LAS __attribute__((address_space(3)))
; __device__ __forceinline__ float ex2(float x) { return __builtin_amdgcn_exp2f(x); }
; __device__ __forceinline__ f32x4 mfma16(bf16x8 a, bf16x8 b, f32x4 c) { return __builtin_amdgcn_mfma_f32_16x16x32_bf16(a, b, c, 0, 0, 0); }
;   __device__ __forceinline__ bf16_t* W() const { return (bf16_t*)(ws + WS_W); }
; template <int NT, int NKK, int NDT, int MODE, bool MASK> ...
;     ...
;   f32x4 s[NT][4];
;   __builtin_amdgcn_s_setprio(1);
; #pragma unroll
;   for (int t = 0; t < 4; ++t)
; #pragma unroll
;     for (int kk = 0; kk < NKK; ++kk) {
;       const bf16x8 kf = *(LAS const bf16x8*)(Kl + (16 * t + r) * KSTR + (32 * kk + 8 * lg) * 2);
; #pragma unroll
;       for (int j = 0; j < NT; ++j) s[j][t] = mfma16(kf, qf[j][kk], kk == 0 ? (f32x4){0.f, 0.f, 0.f, 0.f} : s[j][t]);
;     }
;   __builtin_amdgcn_s_setprio(0);
;   bf16x8 pf[NT][2];
; #pragma unroll
;   for (int j = 0; j < NT; ++j) {
;     float mx = -INFINITY;
; #pragma unroll
;     for (int t = 0; t < 4; ++t)
; #pragma unroll
;       for (int i = 0; i < 4; ++i) {
;         if (MASK) { const int kp = kpos0 + 16 * t + 4 * lg + i; if (!mask_ok<MODE>(tq[j], kp, W)) s[j][t][i] = -INFINITY; }
;         mx = fmaxf(mx, s[j][t][i]);
;       }
;     mx = max_x16_x32(mx);
;     if (__any(mx > m[j] + 8.0f / c)) {
;       const float mnew = fmaxf(m[j], mx);
;       const float ms2 = (mnew == -INFINITY) ? 0.f : mnew;
;       const float alpha = ex2((m[j] - ms2) * c);
;       m[j] = mnew; l[j] *= alpha;
; #pragma unroll
;       for (int dt = 0; dt < NDT; ++dt) o[j][dt] *= alpha;
;     }
;     const float mc = ((m[j] == -INFINITY) ? 0.f : m[j]) * c;
.LBB0_983:
	s_waitcnt lgkmcnt(0)
	s_barrier
	s_add_i32 s8, s43, 0xffffff81
	s_cmp_gt_i32 s8, s40
	s_cbranch_scc1 .LBB0_1010
	s_sub_i32 s8, s43, 64
	s_cmp_gt_i32 s8, s25
	s_setprio 1
	v_add_u32_e32 v1, s59, v236
	s_waitcnt lgkmcnt(0)
	v_add_u32_e32 v94, v1, v237
	ds_read_b128 v[134:137], v94
	ds_read_b128 v[130:133], v94 offset:64
	ds_read_b128 v[126:129], v94 offset:128
	ds_read_b128 v[122:125], v94 offset:3328
	ds_read_b128 v[118:121], v94 offset:3392
	ds_read_b128 v[114:117], v94 offset:3456
	ds_read_b128 v[106:109], v94 offset:6656
	ds_read_b128 v[98:101], v94 offset:6720
	v_add_u32_e32 v201, v1, v238
	ds_read_b128 v[110:113], v94 offset:6784
	ds_read_b128 v[102:105], v201
	ds_read_b128 v[94:97], v201 offset:64
	s_mov_b64 s[20:21], -1
	v_add_f32_e32 v1, 0x4259535f, v220
	s_cbranch_scc1 .LBB0_1001
	s_waitcnt lgkmcnt(10)
	v_mfma_f32_16x16x32_bf16 v[138:141], v[134:137], v[18:21], 0
	ds_read_b128 v[146:149], v201 offset:128
	v_mov_b32_e32 v234, 0x260
	v_mfma_f32_16x16x32_bf16 v[142:145], v[134:137], v[10:13], 0
	s_waitcnt lgkmcnt(10)
	v_mfma_f32_16x16x32_bf16 v[138:141], v[130:133], v[2:5], v[138:141]
	v_mov_b64_e32 v[222:223], v[220:221]
	v_mfma_f32_16x16x32_bf16 v[142:145], v[130:133], v[14:17], v[142:145]
	v_mov_b64_e32 v[224:225], v[218:219]
	s_waitcnt lgkmcnt(9)
	v_mfma_f32_16x16x32_bf16 v[182:185], v[126:129], v[6:9], v[138:141]
	v_mfma_f32_16x16x32_bf16 v[166:169], v[126:129], v[22:25], v[142:145]
	v_mov_b32_e32 v187, v220
	s_waitcnt lgkmcnt(8)
	v_mfma_f32_16x16x32_bf16 v[138:141], v[122:125], v[18:21], 0
	v_add_f32_e32 v158, 0x4259535f, v221
	v_mfma_f32_16x16x32_bf16 v[142:145], v[122:125], v[10:13], 0
	v_mul_f32_e32 v159, 0x3e16c740, v220
	s_waitcnt lgkmcnt(7)
	v_mfma_f32_16x16x32_bf16 v[138:141], v[118:121], v[2:5], v[138:141]
	v_cmp_neq_f32_e64 s[22:23], s81, v220
	v_mfma_f32_16x16x32_bf16 v[142:145], v[118:121], v[14:17], v[142:145]
	s_waitcnt lgkmcnt(6)
	v_mfma_f32_16x16x32_bf16 v[178:181], v[114:117], v[6:9], v[138:141]
	v_mfma_f32_16x16x32_bf16 v[154:157], v[114:117], v[22:25], v[142:145]
	v_cndmask_b32_e64 v159, 0, v159, s[22:23]
	s_waitcnt lgkmcnt(5)
	v_mfma_f32_16x16x32_bf16 v[138:141], v[106:109], v[18:21], 0
	v_mfma_f32_16x16x32_bf16 v[142:145], v[106:109], v[10:13], 0
	v_max3_f32 v188, v182, s81, v183
	s_waitcnt lgkmcnt(4)
	v_mfma_f32_16x16x32_bf16 v[138:141], v[98:101], v[2:5], v[138:141]
	v_max3_f32 v188, v188, v184, v185
	v_mfma_f32_16x16x32_bf16 v[142:145], v[98:101], v[14:17], v[142:145]
	v_max3_f32 v189, v166, s81, v167
	s_waitcnt lgkmcnt(3)
	v_mfma_f32_16x16x32_bf16 v[174:177], v[110:113], v[6:9], v[138:141]
	v_max3_f32 v189, v189, v168, v169
	v_mfma_f32_16x16x32_bf16 v[150:153], v[110:113], v[22:25], v[142:145]
	s_waitcnt lgkmcnt(2)
	v_mfma_f32_16x16x32_bf16 v[138:141], v[102:105], v[18:21], 0
	v_mfma_f32_16x16x32_bf16 v[142:145], v[102:105], v[10:13], 0
	v_max3_f32 v188, v188, v178, v179
	s_waitcnt lgkmcnt(1)
	v_mfma_f32_16x16x32_bf16 v[138:141], v[94:97], v[2:5], v[138:141]
	v_max3_f32 v188, v188, v180, v181
	v_mfma_f32_16x16x32_bf16 v[142:145], v[94:97], v[14:17], v[142:145]
	v_max3_f32 v189, v189, v154, v155
	s_waitcnt lgkmcnt(0)
	v_mfma_f32_16x16x32_bf16 v[170:173], v[146:149], v[6:9], v[138:141]
	v_max3_f32 v189, v189, v156, v157
	v_mfma_f32_16x16x32_bf16 v[142:145], v[146:149], v[22:25], v[142:145]
	s_setprio 0
	s_nop 3
	v_max3_f32 v138, v188, v174, v175
	v_max3_f32 v138, v138, v176, v177
	v_max3_f32 v138, v138, v170, v171
	v_max3_f32 v138, v138, v172, v173
	v_mov_b32_e32 v139, v138
	s_nop 1
	v_permlane16_swap_b32_e32 v138, v139
	v_max_f32_e32 v138, v138, v139
	v_mov_b32_e32 v139, v138
	s_nop 1
	v_permlane32_swap_b32_e32 v138, v139
	v_max_f32_e32 v186, v138, v139
	v_cmp_gt_f32_e32 vcc, v186, v1
	s_cbranch_vccz .LBB0_987
	v_max_f32_e32 v138, v186, v186
	v_max_f32_e32 v139, v220, v220
	v_max_f32_e32 v222, v139, v138
	v_cmp_neq_f32_e32 vcc, s81, v222
	v_mov_b32_e32 v223, v221
	v_mov_b32_e32 v225, v219
	v_cndmask_b32_e32 v138, 0, v222, vcc
	v_sub_f32_e32 v138, v220, v138
	v_mul_f32_e32 v138, 0x3e16c740, v138
	v_exp_f32_e32 v138, v138
	v_mov_b32_e32 v187, v222
	v_mul_f32_e32 v224, v218, v138
	v_pk_mul_f32 v[92:93], v[92:93], v[138:139] op_sel_hi:[1,0]
	v_pk_mul_f32 v[90:91], v[90:91], v[138:139] op_sel_hi:[1,0]
	v_pk_mul_f32 v[88:89], v[88:89], v[138:139] op_sel_hi:[1,0]
	v_pk_mul_f32 v[86:87], v[86:87], v[138:139] op_sel_hi:[1,0]
	v_pk_mul_f32 v[76:77], v[76:77], v[138:139] op_sel_hi:[1,0]
	v_pk_mul_f32 v[74:75], v[74:75], v[138:139] op_sel_hi:[1,0]
	v_pk_mul_f32 v[68:69], v[68:69], v[138:139] op_sel_hi:[1,0]
	v_pk_mul_f32 v[66:67], v[66:67], v[138:139] op_sel_hi:[1,0]
	v_mul_f32_e32 v159, 0x3e16c740, v187
	v_cmp_neq_f32_e32 vcc, s81, v187
	s_nop 1
	v_cndmask_b32_e32 v159, 0, v159, vcc

; #define LAS __attribute__((address_space(3)))
; __device__ __forceinline__ float ex2(float x) { return __builtin_amdgcn_exp2f(x); }
; __device__ __forceinline__ f32x4 mfma16(bf16x8 a, bf16x8 b, f32x4 c) { return __builtin_amdgcn_mfma_f32_16x16x32_bf16(a, b, c, 0, 0, 0); }
;   __device__ __forceinline__ bf16_t* W() const { return (bf16_t*)(ws + WS_W); }
; template <int NT, int NKK, int NDT, int MODE, bool MASK> ...
;     ...
;   f32x4 s[NT][4];
;   __builtin_amdgcn_s_setprio(1);
; #pragma unroll
;   for (int t = 0; t < 4; ++t)
; #pragma unroll
;     for (int kk = 0; kk < NKK; ++kk) {
;       const bf16x8 kf = *(LAS const bf16x8*)(Kl + (16 * t + r) * KSTR + (32 * kk + 8 * lg) * 2);
; #pragma unroll
;       for (int j = 0; j < NT; ++j) s[j][t] = mfma16(kf, qf[j][kk], kk == 0 ? (f32x4){0.f, 0.f, 0.f, 0.f} : s[j][t]);
;     }
;   __builtin_amdgcn_s_setprio(0);
;   bf16x8 pf[NT][2];
; #pragma unroll
;   for (int j = 0; j < NT; ++j) {
;     float mx = -INFINITY;
; #pragma unroll
;     for (int t = 0; t < 4; ++t)
; #pragma unroll
;       for (int i = 0; i < 4; ++i) {
;         if (MASK) { const int kp = kpos0 + 16 * t + 4 * lg + i; if (!mask_ok<MODE>(tq[j], kp, W)) s[j][t][i] = -INFINITY; }
;         mx = fmaxf(mx, s[j][t][i]);
;       }
;     mx = max_x16_x32(mx);
;     if (__any(mx > m[j] + 8.0f / c)) {
;       const float mnew = fmaxf(m[j], mx);
;       const float ms2 = (mnew == -INFINITY) ? 0.f : mnew;
;       const float alpha = ex2((m[j] - ms2) * c);
;       m[j] = mnew; l[j] *= alpha;
; #pragma unroll
;       for (int dt = 0; dt < NDT; ++dt) o[j][dt] *= alpha;
;     }
;     const float mc = ((m[j] == -INFINITY) ? 0.f : m[j]) * c;
.LBB0_1023:
	s_waitcnt lgkmcnt(0)
	s_barrier
	s_sub_i32 s8, s43, 63
	s_cmp_gt_i32 s8, s40
	s_cbranch_scc1 .LBB0_1050
	s_cmp_gt_i32 s43, s25
	s_setprio 1
	v_add_u32_e32 v1, s45, v236
	s_waitcnt lgkmcnt(0)
	v_add_u32_e32 v94, v1, v237
	ds_read_b128 v[134:137], v94
	ds_read_b128 v[130:133], v94 offset:64
	ds_read_b128 v[126:129], v94 offset:128
	ds_read_b128 v[122:125], v94 offset:3328
	ds_read_b128 v[118:121], v94 offset:3392
	ds_read_b128 v[114:117], v94 offset:3456
	ds_read_b128 v[106:109], v94 offset:6656
	ds_read_b128 v[98:101], v94 offset:6720
	v_add_u32_e32 v201, v1, v238
	ds_read_b128 v[110:113], v94 offset:6784
	ds_read_b128 v[102:105], v201
	ds_read_b128 v[94:97], v201 offset:64
	s_mov_b64 s[20:21], -1
	v_add_f32_e32 v1, 0x4259535f, v220
	s_cbranch_scc1 .LBB0_1041
	s_waitcnt lgkmcnt(10)
	v_mfma_f32_16x16x32_bf16 v[138:141], v[134:137], v[18:21], 0
	ds_read_b128 v[146:149], v201 offset:128
	v_mov_b32_e32 v234, 0x260
	v_mfma_f32_16x16x32_bf16 v[142:145], v[134:137], v[10:13], 0
	s_waitcnt lgkmcnt(10)
	v_mfma_f32_16x16x32_bf16 v[138:141], v[130:133], v[2:5], v[138:141]
	v_mov_b64_e32 v[222:223], v[220:221]
	v_mfma_f32_16x16x32_bf16 v[142:145], v[130:133], v[14:17], v[142:145]
	v_mov_b64_e32 v[224:225], v[218:219]
	s_waitcnt lgkmcnt(9)
	v_mfma_f32_16x16x32_bf16 v[182:185], v[126:129], v[6:9], v[138:141]
	v_mfma_f32_16x16x32_bf16 v[166:169], v[126:129], v[22:25], v[142:145]
	v_mov_b32_e32 v187, v220
	s_waitcnt lgkmcnt(8)
	v_mfma_f32_16x16x32_bf16 v[138:141], v[122:125], v[18:21], 0
	v_add_f32_e32 v158, 0x4259535f, v221
	v_mfma_f32_16x16x32_bf16 v[142:145], v[122:125], v[10:13], 0
	v_mul_f32_e32 v159, 0x3e16c740, v220
	s_waitcnt lgkmcnt(7)
	v_mfma_f32_16x16x32_bf16 v[138:141], v[118:121], v[2:5], v[138:141]
	v_cmp_neq_f32_e64 s[22:23], s81, v220
	v_mfma_f32_16x16x32_bf16 v[142:145], v[118:121], v[14:17], v[142:145]
	s_waitcnt lgkmcnt(6)
	v_mfma_f32_16x16x32_bf16 v[178:181], v[114:117], v[6:9], v[138:141]
	v_mfma_f32_16x16x32_bf16 v[154:157], v[114:117], v[22:25], v[142:145]
	v_cndmask_b32_e64 v159, 0, v159, s[22:23]
	s_waitcnt lgkmcnt(5)
	v_mfma_f32_16x16x32_bf16 v[138:141], v[106:109], v[18:21], 0
	v_mfma_f32_16x16x32_bf16 v[142:145], v[106:109], v[10:13], 0
	v_max3_f32 v188, v182, s81, v183
	s_waitcnt lgkmcnt(4)
	v_mfma_f32_16x16x32_bf16 v[138:141], v[98:101], v[2:5], v[138:141]
	v_max3_f32 v188, v188, v184, v185
	v_mfma_f32_16x16x32_bf16 v[142:145], v[98:101], v[14:17], v[142:145]
	v_max3_f32 v189, v166, s81, v167
	s_waitcnt lgkmcnt(3)
	v_mfma_f32_16x16x32_bf16 v[174:177], v[110:113], v[6:9], v[138:141]
	v_max3_f32 v189, v189, v168, v169
	v_mfma_f32_16x16x32_bf16 v[150:153], v[110:113], v[22:25], v[142:145]
	s_waitcnt lgkmcnt(2)
	v_mfma_f32_16x16x32_bf16 v[138:141], v[102:105], v[18:21], 0
	v_mfma_f32_16x16x32_bf16 v[142:145], v[102:105], v[10:13], 0
	v_max3_f32 v188, v188, v178, v179
	s_waitcnt lgkmcnt(1)
	v_mfma_f32_16x16x32_bf16 v[138:141], v[94:97], v[2:5], v[138:141]
	v_max3_f32 v188, v188, v180, v181
	v_mfma_f32_16x16x32_bf16 v[142:145], v[94:97], v[14:17], v[142:145]
	v_max3_f32 v189, v189, v154, v155
	s_waitcnt lgkmcnt(0)
	v_mfma_f32_16x16x32_bf16 v[170:173], v[146:149], v[6:9], v[138:141]
	v_max3_f32 v189, v189, v156, v157
	v_mfma_f32_16x16x32_bf16 v[142:145], v[146:149], v[22:25], v[142:145]
	s_setprio 0
	s_nop 3
	v_max3_f32 v138, v188, v174, v175
	v_max3_f32 v138, v138, v176, v177
	v_max3_f32 v138, v138, v170, v171
	v_max3_f32 v138, v138, v172, v173
	v_mov_b32_e32 v139, v138
	s_nop 1
	v_permlane16_swap_b32_e32 v138, v139
	v_max_f32_e32 v138, v138, v139
	v_mov_b32_e32 v139, v138
	s_nop 1
	v_permlane32_swap_b32_e32 v138, v139
	v_max_f32_e32 v186, v138, v139
	v_cmp_gt_f32_e32 vcc, v186, v1
	s_cbranch_vccz .LBB0_1027
	v_max_f32_e32 v138, v186, v186
	v_max_f32_e32 v139, v220, v220
	v_max_f32_e32 v222, v139, v138
	v_cmp_neq_f32_e32 vcc, s81, v222
	v_mov_b32_e32 v223, v221
	v_mov_b32_e32 v225, v219
	v_cndmask_b32_e32 v138, 0, v222, vcc
	v_sub_f32_e32 v138, v220, v138
	v_mul_f32_e32 v138, 0x3e16c740, v138
	v_exp_f32_e32 v138, v138
	v_mov_b32_e32 v187, v222
	v_mul_f32_e32 v224, v218, v138
	v_pk_mul_f32 v[92:93], v[92:93], v[138:139] op_sel_hi:[1,0]
	v_pk_mul_f32 v[90:91], v[90:91], v[138:139] op_sel_hi:[1,0]
	v_pk_mul_f32 v[88:89], v[88:89], v[138:139] op_sel_hi:[1,0]
	v_pk_mul_f32 v[86:87], v[86:87], v[138:139] op_sel_hi:[1,0]
	v_pk_mul_f32 v[76:77], v[76:77], v[138:139] op_sel_hi:[1,0]
	v_pk_mul_f32 v[74:75], v[74:75], v[138:139] op_sel_hi:[1,0]
	v_pk_mul_f32 v[68:69], v[68:69], v[138:139] op_sel_hi:[1,0]
	v_pk_mul_f32 v[66:67], v[66:67], v[138:139] op_sel_hi:[1,0]
	v_mul_f32_e32 v159, 0x3e16c740, v187
	v_cmp_neq_f32_e32 vcc, s81, v187
	s_nop 1
	v_cndmask_b32_e32 v159, 0, v159, vcc
